# patch loops: closed-form unit order (shifts instead of a division sequence); FFN epilogue: rinv tag read merged with the taps tag reads
# baseline (speedup 1.0000x reference)
; #define LAS __attribute__((address_space(3)))
; __device__ __forceinline__ int lane_id_hw() { int l; asm volatile("v_mbcnt_lo_u32_b32 %0, -1, 0\n\tv_mbcnt_hi_u32_b32 %0, -1, %0" : "=v"(l)); return l; }
;     __device__ __forceinline__ void operator()(f32x4 (&acc)[2][2][4][2], const Unit& u, int wr, int wc, int fr, int fq, int next_pn) const {
;         { const int l_ = lane_id_hw(); fr = l_ & 15; fq = l_ >> 4; }
;         const int rl0 = wr * 64 + 4 * fr, tcol = wc * 32 + 8 * fq, c0 = u.pn * 128 + tcol;
;         LAS float* R = H + 3 * 2 * 256; LAS float* WL0 = R + 256 + 64; volatile LAS int* wtag = (volatile LAS int*)(R + 256 + 16);
;         const int t2 = ((4 * wr + wc) * 64 + fq * 16 + fr) * 2, wk = t2 >> 8, wtc = t2 & 255, wl_idx = t2;
;         const int tag0 = wtag[0], tag1 = wtag[1];
;         const int bcur = (tag1 == u.pn) ? 1 : 0; const bool have = (tag0 == u.pn) || (tag1 == u.pn);
;         LAS float* WL = WL0 + bcur * 1024;
;         f32x2v wl2 = {0.f, 0.f}, wn2 = {0.f, 0.f};
;         if (!have) { const float* src = (wk < 3 ? cw + wk * 5632 : cb) + (wtc >> 7) * FFW + u.pn * 128 + (wtc & 127); wl2 = *(const f32x2v*)src; }
;         if (next_pn >= 0) { const float* src = (wk < 3 ? cw + wk * 5632 : cb) + (wtc >> 7) * FFW + next_pn * 128 + (wtc & 127); wn2 = *(const f32x2v*)src; }
.LBB0_655:
	v_mbcnt_lo_u32_b32 v207, -1, 0
	v_mbcnt_hi_u32_b32 v207, -1, v207
	v_readlane_b32 s2, v253, 44
	v_and_b32_e32 v0, -16, v207
	v_and_b32_e32 v206, 15, v207
	v_add_u32_e32 v0, s69, v0
	v_or_b32_e32 v130, v0, v206
	v_lshlrev_b32_e32 v208, 1, v130
	v_mov_b32_e32 v130, s83
	v_mov_b32_e32 v131, s2
	ds_read_b32 v130, v130
	ds_read_b32 v131, v131
	v_mov_b32_e32 v216, 0x22000
	ds_read_b32 v216, v216
	v_ashrrev_i32_e32 v134, 7, v0
	v_and_b32_e32 v0, 0xfe, v208
	v_lshrrev_b32_e32 v0, 7, v0
	s_waitcnt lgkmcnt(0)
	v_cmp_eq_u32_e32 vcc, s51, v130
	v_cmp_eq_u32_e64 s[6:7], s51, v131
	s_or_b64 s[44:45], vcc, s[6:7]
	v_and_b32_e32 v130, 0x7e, v208
	s_lshl_b32 s10, s51, 7
	v_mov_b32_e32 v192, 0
	s_and_b64 vcc, exec, s[44:45]
	v_cmp_gt_i32_e64 s[8:9], 3, v134
	v_mul_lo_u32 v132, v134, s77
	v_mul_u32_u24_e32 v135, 0xb00, v0
	v_lshlrev_b32_e32 v130, 2, v130
	v_mov_b32_e32 v138, 0
	v_mov_b32_e32 v139, 0
	s_cbranch_vccnz .LBB0_657
	v_ashrrev_i32_e32 v133, 31, v132
	v_lshl_add_u64 v[136:137], v[132:133], 2, s[22:23]
	v_mov_b32_e32 v0, s59
	v_cndmask_b32_e64 v137, v0, v137, s[8:9]
	v_mov_b32_e32 v0, s58
	v_cndmask_b32_e64 v136, v0, v136, s[8:9]
	v_lshlrev_b32_e32 v0, 2, v135
	v_lshl_add_u64 v[136:137], v[136:137], 0, v[0:1]
	s_ashr_i32 s11, s10, 31
	v_lshl_add_u64 v[136:137], s[10:11], 2, v[136:137]
	v_mov_b32_e32 v131, v1
	v_lshl_add_u64 v[136:137], v[136:137], 0, v[130:131]
	global_load_dwordx2 v[138:139], v[136:137], off

; #define LAS __attribute__((address_space(3)))
; __device__ __forceinline__ int lane_id_hw() { int l; asm volatile("v_mbcnt_lo_u32_b32 %0, -1, 0\n\tv_mbcnt_hi_u32_b32 %0, -1, %0" : "=v"(l)); return l; }
;     __device__ __forceinline__ void operator()(f32x4 (&acc)[2][2][4][2], const Unit& u, int wr, int wc, int fr, int fq, int next_pn) const {
;     ...
;         if (*(volatile LAS int*)(R + 256) != u.pm) {
;             const int wv = 4 * wr + wc, l_ = lane_id_hw(); if (wv < 4) { const int r = wv * 64 + l_; R[r] = rsqrtf(sum16(ss + (size_t)(u.pm * BM + r) * 16) * (1.0f / 1024.0f) + EPS); }
;             asm volatile("s_waitcnt lgkmcnt(0)" ::: "memory"); __builtin_amdgcn_s_barrier(); asm volatile("" ::: "memory");
;             if (wv == 0 && l_ == 0) *(volatile LAS int*)(R + 256) = u.pm; }
.LBB0_659:
	s_add_i32 s11, 0, 0x22000
	v_mov_b32_e32 v0, v216
	v_cmp_eq_u32_e32 vcc, s89, v0
	s_cbranch_vccnz .LBB0_665
	s_andn2_b64 vcc, exec, s[28:29]
	v_mbcnt_lo_u32_b32 v0, -1, 0
	v_mbcnt_hi_u32_b32 v0, -1, v0
	s_cbranch_vccnz .LBB0_662
	v_add_u32_e32 v150, s69, v0
	v_lshl_add_u32 v130, s89, 8, v150
	v_ashrrev_i32_e32 v131, 31, v130
	v_readlane_b32 s8, v254, 51
	v_lshlrev_b64 v[130:131], 6, v[130:131]
	v_readlane_b32 s9, v254, 52
	s_nop 1
	v_lshl_add_u64 v[144:145], s[8:9], 0, v[130:131]
	global_load_dwordx4 v[130:133], v[144:145], off
	global_load_dwordx4 v[134:137], v[144:145], off offset:32
	global_load_dwordx4 v[140:143], v[144:145], off offset:16
	s_nop 0
	global_load_dwordx4 v[144:147], v[144:145], off offset:48
	s_waitcnt vmcnt(0) lgkmcnt(0)
	v_mov_b32_e32 v148, v130
	v_mov_b32_e32 v149, v134
	v_mov_b32_e32 v134, v131
	v_mov_b32_e32 v130, v132
	v_mov_b32_e32 v131, v136
	v_mov_b32_e32 v136, v133
	v_mov_b32_e32 v132, v140
	v_mov_b32_e32 v133, v144
	v_mov_b32_e32 v144, v141
	v_mov_b32_e32 v140, v142
	v_mov_b32_e32 v141, v146
	v_mov_b32_e32 v146, v143
	v_pk_add_f32 v[134:135], v[148:149], v[134:135]
	v_pk_add_f32 v[130:131], v[130:131], v[136:137]
	v_pk_add_f32 v[132:133], v[132:133], v[144:145]
	v_pk_add_f32 v[136:137], v[140:141], v[146:147]
	v_pk_add_f32 v[130:131], v[134:135], v[130:131]
	v_pk_add_f32 v[132:133], v[132:133], v[136:137]
	s_nop 0
	v_pk_add_f32 v[130:131], v[130:131], v[132:133]
	s_nop 0
	v_add_f32_e32 v130, v130, v131
	v_fmamk_f32 v130, v130, 0x3a800000, v240
	v_mul_f32_e32 v131, 0x4b800000, v130
	v_cmp_gt_f32_e32 vcc, s96, v130
	s_nop 1
	v_cndmask_b32_e32 v130, v130, v131, vcc
	v_rsq_f32_e32 v130, v130
	v_lshl_add_u32 v131, v150, 2, 0
	v_add_u32_e32 v131, 0x21c00, v131
	v_mul_f32_e32 v132, 0x45800000, v130
	v_cndmask_b32_e32 v130, v130, v132, vcc
	ds_write_b32 v131, v130
